# v43 + RWKV pass-B decay scalar ds_read_b32 issued at the segment start (right after the barrier) instead of immediately before its use
# baseline (speedup 1.0000x reference)
; template <bool PA> ...
;     ...
;             mm2(Xacc, MAT(10), MAT(6), mt, ntb, r16, kq);
;             st_tr(MAT(7), Xacc, mt, ntb, r16, kq);
;             if (PA) st_tr(MAT(11), X2acc, mt, ntb, r16, kq);
;             __syncthreads();
;             tmp[0] = z4; tmp[1] = z4; mm2(tmp, Tm, MAT(7), mt, ntb, r16, kq);
;             st_tr(MAT(8), tmp, mt, ntb, r16, kq);
;             if (PA) { tmp[0] = z4; tmp[1] = z4; mm2(tmp, MAT(3), MAT(11), mt, ntb, r16, kq); st_tr(MAT(12), tmp, mt, ntb, r16, kq); }
;             __syncthreads();
;             if (!PA) { mm2(Yacc, MAT(11), MAT(8), mt, ntb, r16, kq); mm2(Yacc, MAT(12), MAT(6), mt, ntb, r16, kq);
;             st_rm(MAT(7), Yacc, mt, ntb, r16, kq); }
;             if (PA) mm2(S2acc, MAT(12), MAT(4), mt, ntb, r16, kq);
;             mm2(Sacc, MAT(8), MAT(4), mt, ntb, r16, kq); mm2(Sacc, MAT(6), MAT(5), mt, ntb, r16, kq);
; #pragma unroll
;             for (int i = 0; i < 2; ++i) { const float wk = wc[16 * (ntb + i) + r16];
; #pragma unroll
;                 for (int e = 0; e < 4; ++e) { Sacc[i][e] *= wk; S2acc[i][e] *= wk; } }
;             __syncthreads();
.LBB0_245:
	s_or_b64 exec, exec, s[12:13]
	ds_read_b128 v[26:29], v128
	ds_read_b128 v[30:33], v118 offset:55296
	ds_read_b128 v[186:189], v118 offset:57600
	ds_read_b128 v[190:193], v128 offset:64
	ds_read_b128 v[204:207], v118 offset:55360
	ds_read_b128 v[208:211], v118 offset:57664
	s_add_i32 s20, s20, 1
	s_add_i32 s24, s24, -1
	v_lshl_add_u64 v[100:101], v[100:101], 0, s[34:35]
	s_cmp_ge_i32 s20, s21
	s_waitcnt lgkmcnt(4)
	v_mfma_f32_16x16x32_bf16 v[22:25], v[26:29], v[30:33], v[22:25]
	s_waitcnt lgkmcnt(3)
	v_mfma_f32_16x16x32_bf16 v[18:21], v[26:29], v[186:189], v[18:21]
	s_waitcnt lgkmcnt(1)
	v_mfma_f32_16x16x32_bf16 v[22:25], v[190:193], v[204:207], v[22:25]
	s_waitcnt lgkmcnt(0)
	v_mfma_f32_16x16x32_bf16 v[18:21], v[190:193], v[208:211], v[18:21]
	s_nop 4
	v_cvt_pk_bf16_f32 v22, v22, v23
	v_cvt_pk_bf16_f32 v23, v24, v25
	ds_write_b64 v127, v[22:23] offset:64512
	v_cvt_pk_bf16_f32 v18, v18, v19
	v_cvt_pk_bf16_f32 v19, v20, v21
	ds_write_b64 v129, v[18:19]
	v_cvt_pk_bf16_f32 v18, v46, v47
	v_cvt_pk_bf16_f32 v19, v48, v49
	ds_write_b64 v130, v[18:19]
	v_cvt_pk_bf16_f32 v18, v42, v43
	v_cvt_pk_bf16_f32 v19, v44, v45
	ds_write_b64 v130, v[18:19] offset:2304
	s_waitcnt lgkmcnt(0)
	s_barrier
	ds_read_b128 v[186:189], v69 offset:27648
	ds_read_b128 v[190:193], v118 offset:64512
	ds_read_b128 v[204:207], v123
	ds_read_b128 v[208:211], v69 offset:27712
	ds_read_b128 v[212:215], v118 offset:64576
	ds_read_b128 v[216:219], v124
	ds_read_b128 v[220:223], v69 offset:27648
	ds_read_b128 v[224:227], v132
	s_nop 0
	s_nop 0
	s_nop 0
	s_waitcnt lgkmcnt(6)
	v_mfma_f32_16x16x32_bf16 v[22:25], v[186:189], v[190:193], 0
	ds_read_b128 v[190:193], v132 offset:2304
	s_waitcnt lgkmcnt(6)
	v_mfma_f32_16x16x32_bf16 v[18:21], v[186:189], v[204:207], 0
	ds_read_b128 v[186:189], v69 offset:27712
	ds_read_b128 v[204:207], v132 offset:64
	s_nop 0
	s_nop 0
	s_waitcnt lgkmcnt(6)
	v_mfma_f32_16x16x32_bf16 v[22:25], v[208:211], v[212:215], v[22:25]
	ds_read_b128 v[212:215], v132 offset:2368
	s_nop 0
	s_waitcnt lgkmcnt(6)
	v_mfma_f32_16x16x32_bf16 v[18:21], v[208:211], v[216:219], v[18:21]
	s_nop 4
	v_cvt_pk_bf16_f32 v22, v22, v23
	v_cvt_pk_bf16_f32 v23, v24, v25
	ds_write_b64 v131, v[22:23]
	v_cvt_pk_bf16_f32 v18, v18, v19
	v_cvt_pk_bf16_f32 v19, v20, v21
	ds_write_b64 v131, v[18:19] offset:2304
	s_nop 0
	s_nop 0
	s_nop 0
	s_waitcnt lgkmcnt(0)
	v_mfma_f32_16x16x32_bf16 v[22:25], v[220:223], v[224:227], 0
	s_waitcnt lgkmcnt(0)
	v_mfma_f32_16x16x32_bf16 v[18:21], v[220:223], v[190:193], 0
	s_nop 0
	s_nop 0
	s_waitcnt lgkmcnt(0)
	v_mfma_f32_16x16x32_bf16 v[22:25], v[186:189], v[204:207], v[22:25]
	s_nop 0
	s_waitcnt lgkmcnt(0)
	v_mfma_f32_16x16x32_bf16 v[18:21], v[186:189], v[212:215], v[18:21]
	s_nop 4
	v_cvt_pk_bf16_f32 v22, v22, v23
	v_cvt_pk_bf16_f32 v23, v24, v25
	ds_write_b64 v133, v[22:23]
	v_cvt_pk_bf16_f32 v18, v18, v19
	v_cvt_pk_bf16_f32 v19, v20, v21
	ds_write_b64 v133, v[18:19] offset:2304
	s_waitcnt lgkmcnt(0)
	s_barrier
	ds_read_b32 v0, v157
	ds_read_b128 v[186:189], v134
	ds_read_b128 v[190:193], v118 offset:36864
	ds_read_b128 v[204:207], v118 offset:39168
	ds_read_b128 v[208:211], v134 offset:64
	ds_read_b128 v[212:215], v118 offset:36928
	ds_read_b128 v[216:219], v118 offset:39232
	ds_read_b128 v[220:223], v125
	ds_read_b128 v[224:227], v125 offset:64
	s_nop 0
	s_nop 0
	s_nop 0
	s_waitcnt lgkmcnt(6)
	v_mfma_f32_16x16x32_bf16 v[10:13], v[186:189], v[190:193], v[10:13]
	s_waitcnt lgkmcnt(5)
	v_mfma_f32_16x16x32_bf16 v[14:17], v[186:189], v[204:207], v[14:17]
	ds_read_b128 v[186:189], v69 offset:55296
	s_nop 0
	s_nop 0
	s_nop 0
	s_waitcnt lgkmcnt(4)
	v_mfma_f32_16x16x32_bf16 v[10:13], v[208:211], v[212:215], v[10:13]
	s_waitcnt lgkmcnt(3)
	v_mfma_f32_16x16x32_bf16 v[14:17], v[208:211], v[216:219], v[14:17]
	ds_read_b128 v[208:211], v118 offset:46080
	s_nop 0
	s_waitcnt lgkmcnt(3)
	v_mfma_f32_16x16x32_bf16 v[2:5], v[220:223], v[190:193], v[2:5]
	ds_read_b128 v[190:193], v118 offset:48384
	v_mfma_f32_16x16x32_bf16 v[6:9], v[220:223], v[204:207], v[6:9]
	v_mov_b32_e32 v26, v204
	v_mov_b32_e32 v27, v205
	v_mov_b32_e32 v28, v206
	v_mov_b32_e32 v29, v207
	ds_read_b128 v[204:207], v69 offset:55360
	ds_read_b128 v[220:223], v118 offset:46144
	s_nop 0
	s_waitcnt lgkmcnt(5)
	v_mfma_f32_16x16x32_bf16 v[2:5], v[224:227], v[212:215], v[2:5]
	v_mov_b32_e32 v30, v212
	v_mov_b32_e32 v31, v213
	v_mov_b32_e32 v32, v214
	v_mov_b32_e32 v33, v215
	ds_read_b128 v[212:215], v118 offset:48448
	v_mfma_f32_16x16x32_bf16 v[6:9], v[224:227], v[216:219], v[6:9]
	v_mov_b32_e32 v34, v216
	v_mov_b32_e32 v35, v217
	v_mov_b32_e32 v36, v218
	v_mov_b32_e32 v37, v219
	s_nop 0
	s_nop 0
	s_waitcnt lgkmcnt(4)
	v_mfma_f32_16x16x32_bf16 v[2:5], v[186:189], v[208:211], v[2:5]
	s_nop 0
	s_waitcnt lgkmcnt(3)
	v_mfma_f32_16x16x32_bf16 v[6:9], v[186:189], v[190:193], v[6:9]
	s_nop 0
	s_nop 0
	s_waitcnt lgkmcnt(0)
	v_pk_mul_f32 v[12:13], v[12:13], v[0:1] op_sel_hi:[1,0]
	v_mfma_f32_16x16x32_bf16 v[2:5], v[204:207], v[220:223], v[2:5]
	s_nop 0
	v_pk_mul_f32 v[10:11], v[10:11], v[0:1] op_sel_hi:[1,0]
	s_waitcnt lgkmcnt(0)
	v_mfma_f32_16x16x32_bf16 v[6:9], v[204:207], v[212:215], v[6:9]
	v_mov_b32_e32 v18, v204
	v_mov_b32_e32 v19, v205
	v_mov_b32_e32 v20, v206
	v_mov_b32_e32 v21, v207
	v_mov_b32_e32 v22, v212
	v_mov_b32_e32 v23, v213
	v_mov_b32_e32 v24, v214
	v_mov_b32_e32 v25, v215
	s_nop 3
	v_mul_f32_e64 v2, v2, v0
	v_mul_f32_e64 v3, v3, v0
	v_pk_mul_f32 v[4:5], v[4:5], v[0:1] op_sel_hi:[1,0]
	ds_read_b32 v0, v158
	s_waitcnt lgkmcnt(0)
	s_barrier
	v_pk_mul_f32 v[6:7], v[6:7], v[0:1] op_sel_hi:[1,0]
	v_pk_mul_f32 v[8:9], v[8:9], v[0:1] op_sel_hi:[1,0]
	v_pk_mul_f32 v[16:17], v[16:17], v[0:1] op_sel_hi:[1,0]
	v_pk_mul_f32 v[14:15], v[14:15], v[0:1] op_sel_hi:[1,0]
	s_cbranch_scc1 .LBB0_193
	v_mov_b32_e32 v0, v9
	s_branch .LBB0_213
